# decode pass 1: xor-16 stage of the per-key halving butterfly via v_permlane16_swap + add (17 of 32 keys), replacing 2 selects + ds_bpermute + wait per exchange
# speedup vs baseline: 1.0009x; 1.0009x over previous
; #define LAS __attribute__((address_space(3)))
; #define DEC_LOADK(dst, i0) do { asm volatile("" ::: "memory"); _Pragma("unroll") for (int u = 0; u < 4; ++u) { const float* kr = ck + rbase + (size_t)((i0) + u) * 512; dst[u][0] = __builtin_nontemporal_load((const f32x4*)(kr + 4 * lane)); dst[u][1] = __builtin_nontemporal_load((const f32x4*)(kr + 256 + 4 * lane)); } } while (0)
; __device__ __forceinline__ void decode_item(Frame& F, const Args& a, int l, int item, unsigned char* ws) {
;     const int sb = item >> 6, seg = item & 63, lane = F.lane, w = F.wave, tid = F.tid;
;     LAS float* OM = (LAS float*)F.lds; LAS float* BT = OM + 256 * 16; LAS float* SEGT = BT + 256 * 16;
;     const float* QS = (const float*)(ws + WS_QS); const int* pt = (const int*)a.in[4] + sb * NPAGES;
;     const float* ck = (const float*)a.in[2] + (size_t)l * NPHYS * 128 * 512; const float* cv = (const float*)a.in[3] + (size_t)l * NPHYS * 128 * 512;
;     const float* bias = (const float*)a.in[17] + l * 4;
;     f32x4 Qr[4][2];
; #pragma unroll
;     for (int qi = 0; qi < 4; ++qi)
; #pragma unroll
;         for (int g = 0; g < 2; ++g) Qr[qi][g] = *(const f32x4*)(QS + (size_t)(sb * 4 + qi) * BW + g * 256 + 4 * lane);
;     const int page = pt[seg * 2 + (w >> 2)];
;     const size_t rbase = ((size_t)page * 128 + (w & 3) * 32) * 512;
;     const int b4 = (lane >> 4) & 1, b3 = (lane >> 3) & 1, b2 = (lane >> 2) & 1;
;     const int vidx = b4 * 4 + b3 * 2 + b2, qi_m = vidx >> 1, head_m = (vidx & 1) * 2 + (lane >> 5);
;     const float bias_m = bias[head_m] * LOG2E;
;     const int pos_m = (head_m & 1) * 8 + qi_m * 2 + (head_m >> 1);
;     {
;         f32x4 ka[4][2], kb[4][2];
;     ...
;         DEC_LOADK(ka, 0); DEC_LOADK(kb, 4); DEC_SCORE(ka, 0); DEC_LOADK(ka, 8); DEC_SCORE(kb, 4); DEC_LOADK(kb, 12); DEC_SCORE(ka, 8); DEC_LOADK(ka, 16); DEC_SCORE(kb, 12); DEC_LOADK(kb, 20); DEC_SCORE(ka, 16); DEC_LOADK(ka, 24); DEC_SCORE(kb, 20); DEC_LOADK(kb, 28); DEC_SCORE(ka, 24); DEC_SCORE(kb, 28);
.LBB0_1149:
	s_lshl_b32 s0, s13, 2
	s_or_b32 s5, s4, s0
	v_readlane_b32 s0, v253, 1
	s_add_i32 s4, s5, s0
	v_lshlrev_b32_e32 v116, 2, v122
	s_ashr_i32 s15, s4, 6
	v_ashrrev_i32_e32 v117, 31, v116
	s_lshl_b32 s16, s15, 2
	v_lshlrev_b64 v[36:37], 2, v[116:117]
	v_lshl_add_u64 v[2:3], s[10:11], 0, v[36:37]
	s_mov_b64 s[24:25], 0x34600000
	s_ashr_i32 s17, s16, 31
	v_lshl_add_u64 v[26:27], v[2:3], 0, s[24:25]
	s_lshl_b64 s[24:25], s[16:17], 11
	v_lshl_add_u64 v[2:3], v[26:27], 0, s[24:25]
	s_or_b32 s24, s16, 1
	s_ashr_i32 s25, s24, 31
	s_lshl_b64 s[24:25], s[24:25], 11
	s_lshl_b32 s6, s15, 7
	v_lshl_add_u64 v[10:11], v[26:27], 0, s[24:25]
	s_or_b32 s24, s16, 2
	s_or_b32 s16, s16, 3
	s_ashr_i32 s7, s6, 31
	s_lshl_b32 s2, s12, 2
	s_ashr_i32 s25, s24, 31
	s_ashr_i32 s17, s16, 31
	v_readlane_b32 s36, v252, 21
	s_ashr_i32 s3, s2, 31
	s_lshl_b64 s[24:25], s[24:25], 11
	s_lshl_b64 s[16:17], s[16:17], 11
	s_lshl_b64 s[6:7], s[6:7], 2
	v_readlane_b32 s44, v252, 29
	s_mul_hi_i32 s1, s12, 0x5000000
	s_mul_i32 s0, s12, 0x5000000
	v_lshl_add_u64 v[18:19], v[26:27], 0, s[24:25]
	v_lshl_add_u64 v[26:27], v[26:27], 0, s[16:17]
	v_readlane_b32 s45, v252, 30
	s_add_u32 s16, s44, s6
	v_readlane_b32 s40, v252, 25
	s_addc_u32 s17, s45, s7
	s_lshl_b64 s[6:7], s[0:1], 2
	v_readlane_b32 s41, v252, 26
	s_add_u32 s0, s40, s6
	s_addc_u32 s1, s41, s7
	s_lshl_b64 s[2:3], s[2:3], 2
	v_readlane_b32 s24, v254, 0
	v_readlane_b32 s25, v254, 1
	s_add_u32 s2, s24, s2
	s_addc_u32 s3, s25, s3
	s_lshl_b32 s5, s5, 1
	s_and_b32 s5, s5, 0x7e
	v_ashrrev_i32_e64 v34, 2, s18
	v_add_u32_e32 v38, s5, v34
	v_ashrrev_i32_e32 v39, 31, v38
	v_lshl_add_u64 v[38:39], v[38:39], 2, s[16:17]
	global_load_dwordx4 v[6:9], v[2:3], off
	s_nop 0
	global_load_dwordx4 v[2:5], v[2:3], off offset:1024
	s_nop 0
	global_load_dwordx4 v[14:17], v[10:11], off
	s_nop 0
	global_load_dwordx4 v[10:13], v[10:11], off offset:1024
	s_nop 0
	global_load_dwordx4 v[22:25], v[18:19], off
	s_nop 0
	global_load_dwordx4 v[18:21], v[18:19], off offset:1024
	s_nop 0
	global_load_dwordx4 v[30:33], v[26:27], off
	s_nop 0
	global_load_dwordx4 v[26:29], v[26:27], off offset:1024
	v_lshlrev_b32_e64 v34, 14, s18
	global_load_dword v38, v[38:39], off
	s_mov_b32 s5, 0xc000
	v_ashrrev_i32_e32 v124, 5, v122
	v_bfe_u32 v94, v122, 4, 1
	v_bfe_u32 v95, v122, 3, 1
	v_lshlrev_b32_e32 v42, 3, v124
	v_lshlrev_b32_e32 v43, 2, v94
	v_lshlrev_b32_e32 v44, 1, v95
	v_and_b32_e32 v106, 64, v218
	v_add_u32_e32 v106, 64, v106
	v_readlane_b32 s42, v252, 27
	v_readlane_b32 s43, v252, 28
	v_readlane_b32 s38, v252, 23
	v_readlane_b32 s39, v252, 24
	v_cmp_eq_u32_e64 s[38:39], 0, v95
	v_readlane_b32 s37, v252, 22
	v_readlane_b32 s46, v252, 31
	v_readlane_b32 s47, v252, 32
	v_readlane_b32 s48, v252, 33
	v_readlane_b32 s49, v252, 34
	v_readlane_b32 s50, v252, 35
	v_readlane_b32 s51, v252, 36
	s_waitcnt vmcnt(0)
	v_ashrrev_i32_e32 v39, 31, v38
	v_lshlrev_b64 v[118:119], 16, v[38:39]
	v_and_or_b32 v118, v34, s5, v118
	v_lshrrev_b32_e32 v34, 1, v122
	v_and_b32_e32 v34, 2, v34
	v_add_u32_e32 v38, v34, v124
	v_ashrrev_i32_e32 v39, 31, v38
	v_lshl_add_u64 v[40:41], v[38:39], 2, s[2:3]
	v_lshl_add_u64 v[92:93], v[118:119], 2, s[0:1]
	global_load_dword v34, v[40:41], off
	v_lshl_add_u64 v[36:37], v[92:93], 0, v[36:37]
	global_load_dwordx4 v[96:99], v[36:37], off nt
	global_load_dwordx4 v[100:103], v[36:37], off offset:1024 nt
	global_load_dwordx4 v[88:91], v[36:37], off offset:2048 nt
	global_load_dwordx4 v[84:87], v[36:37], off offset:3072 nt
	v_ashrrev_i32_e32 v104, 1, v38
	v_add_co_u32_e32 v38, vcc, s69, v36
	s_movk_i32 s0, 0x2000
	s_nop 0
	v_addc_co_u32_e32 v39, vcc, 0, v37, vcc
	v_add_co_u32_e32 v40, vcc, s0, v36
	s_movk_i32 s0, 0x3000
	s_nop 0
	v_addc_co_u32_e32 v41, vcc, 0, v37, vcc
	v_add_co_u32_e32 v36, vcc, s0, v36
	global_load_dwordx4 v[80:83], v[40:41], off offset:-4096 nt
	global_load_dwordx4 v[76:79], v[38:39], off offset:1024 nt
	global_load_dwordx4 v[72:75], v[38:39], off offset:2048 nt
	global_load_dwordx4 v[68:71], v[38:39], off offset:3072 nt
	v_and_b32_e32 v38, 8, v42
	v_addc_co_u32_e32 v37, vcc, 0, v37, vcc
	v_or3_b32 v105, v43, v44, v38
	global_load_dwordx4 v[64:67], v[40:41], off nt
	global_load_dwordx4 v[60:63], v[40:41], off offset:1024 nt
	global_load_dwordx4 v[52:55], v[40:41], off offset:2048 nt
	global_load_dwordx4 v[44:47], v[40:41], off offset:3072 nt
	global_load_dwordx4 v[56:59], v[36:37], off nt
	global_load_dwordx4 v[48:51], v[36:37], off offset:1024 nt
	s_nop 0
	global_load_dwordx4 v[40:43], v[36:37], off offset:2048 nt
	s_nop 0
	global_load_dwordx4 v[36:39], v[36:37], off offset:3072 nt
	v_cmp_eq_u32_e64 s[0:1], 0, v94
	v_xor_b32_e32 v94, 16, v218
	v_cmp_lt_i32_e32 vcc, v94, v106
	s_waitcnt vmcnt(16)
	v_mul_f32_e32 v34, 0x3fb8aa3b, v34
	v_cndmask_b32_e32 v94, v218, v94, vcc
	v_lshlrev_b32_e32 v125, 2, v94
	v_and_b32_e32 v94, 4, v122
	v_cmp_eq_u32_e64 s[42:43], 0, v94
	v_and_b32_e32 v94, 3, v122
	v_cmp_eq_u32_e64 s[44:45], 0, v94
	v_lshlrev_b32_e64 v94, 9, s18
	v_add3_u32 v94, v105, v104, v94
	s_waitcnt vmcnt(15)
	v_pk_mul_f32 v[104:105], v[6:7], v[96:97]
	v_lshl_add_u32 v126, v94, 2, 0
	v_pk_fma_f32 v[104:105], v[98:99], v[8:9], v[104:105]
	s_nop 0
	v_add_f32_e32 v95, v104, v105
	s_waitcnt vmcnt(14)
	v_pk_mul_f32 v[104:105], v[2:3], v[100:101]
	s_nop 0
	v_pk_fma_f32 v[104:105], v[102:103], v[4:5], v[104:105]
	s_nop 0
	v_add_f32_e32 v106, v104, v105
	v_pk_mul_f32 v[104:105], v[14:15], v[96:97]
	s_nop 0
	v_pk_fma_f32 v[104:105], v[98:99], v[16:17], v[104:105]
	s_nop 0
	v_add_f32_e32 v107, v104, v105
	v_pk_mul_f32 v[104:105], v[10:11], v[100:101]
	s_nop 0
	v_pk_fma_f32 v[104:105], v[102:103], v[12:13], v[104:105]
	s_nop 0
	v_add_f32_e32 v108, v104, v105
	v_pk_mul_f32 v[104:105], v[22:23], v[96:97]
	v_pk_mul_f32 v[96:97], v[30:31], v[96:97]
	v_pk_fma_f32 v[104:105], v[98:99], v[24:25], v[104:105]
	v_pk_fma_f32 v[96:97], v[98:99], v[32:33], v[96:97]
	v_add_f32_e32 v109, v104, v105
	v_add_f32_e32 v98, v96, v97
	v_pk_mul_f32 v[96:97], v[26:27], v[100:101]
	v_pk_mul_f32 v[104:105], v[18:19], v[100:101]
	v_pk_fma_f32 v[96:97], v[102:103], v[28:29], v[96:97]
	v_pk_fma_f32 v[104:105], v[102:103], v[20:21], v[104:105]
	v_add_f32_e32 v96, v96, v97
	v_add_f32_e32 v104, v104, v105
	s_waitcnt lgkmcnt(0)
	s_nop 1
	v_permlane16_swap_b32 v95, v109
	v_add_f32_e32 v95, v95, v109
	s_waitcnt lgkmcnt(0)
	s_nop 1
	v_permlane16_swap_b32 v106, v104
	v_add_f32_e32 v97, v106, v104
	s_waitcnt lgkmcnt(0)
	s_nop 1
	v_permlane16_swap_b32 v107, v98
	v_add_f32_e32 v98, v107, v98
	s_waitcnt lgkmcnt(0)
	s_nop 1
	v_permlane16_swap_b32 v108, v96
	v_add_f32_e32 v96, v108, v96
	v_cndmask_b32_e64 v99, v95, v98, s[38:39]
	v_cndmask_b32_e64 v95, v98, v95, s[38:39]
	v_cndmask_b32_e64 v98, v97, v96, s[38:39]
	v_cndmask_b32_e64 v96, v96, v97, s[38:39]
	v_add_f32_dpp v95, v99, v95 row_ror:8 row_mask:0xf bank_mask:0xf bound_ctrl:1
	s_nop 0
	v_add_f32_dpp v96, v98, v96 row_ror:8 row_mask:0xf bank_mask:0xf bound_ctrl:1
	v_cndmask_b32_e64 v97, v95, v96, s[42:43]
	v_cndmask_b32_e64 v95, v96, v95, s[42:43]
	v_mov_b32_e32 v96, v35
	v_mov_b32_e32 v98, v35
	s_nop 0
	v_mov_b32_dpp v96, v97 row_ror:4 row_mask:0xf bank_mask:0xf
	v_mov_b32_dpp v98, v97 row_ror:12 row_mask:0xf bank_mask:0xf
	v_cndmask_b32_e64 v96, v96, v98, s[42:43]
	v_add_f32_e32 v95, v95, v96
	v_mov_b32_e32 v96, 0
	s_nop 0
	v_add_f32_dpp v95, v95, v95 quad_perm:[2,3,0,1] row_mask:0xf bank_mask:0xf bound_ctrl:1
	s_nop 1
	v_mov_b32_dpp v96, v95 quad_perm:[1,0,3,2] row_mask:0xf bank_mask:0xf
	s_and_saveexec_b64 s[2:3], s[44:45]
	s_cbranch_execz .LBB0_1151
	v_add_f32_e32 v94, v95, v96
	v_add_f32_e32 v94, v34, v94
	v_exp_f32_e32 v94, v94
	s_nop 0
	v_add_f32_e32 v95, 1.0, v94
	v_rcp_f32_e32 v95, v95
	s_nop 0
	v_mul_f32_e32 v94, v94, v95
	ds_write2st64_b32 v126, v95, v94 offset1:64
.LBB0_1151:
	s_or_b64 exec, exec, s[2:3]
	s_waitcnt vmcnt(13)
	v_pk_mul_f32 v[94:95], v[6:7], v[88:89]
	s_nop 0
	v_pk_fma_f32 v[94:95], v[90:91], v[8:9], v[94:95]
	s_nop 0
	v_add_f32_e32 v96, v94, v95
	s_waitcnt vmcnt(12)
	v_pk_mul_f32 v[94:95], v[2:3], v[84:85]
	s_nop 0
	v_pk_fma_f32 v[94:95], v[86:87], v[4:5], v[94:95]
	s_nop 0
	v_add_f32_e32 v97, v94, v95
	v_pk_mul_f32 v[94:95], v[14:15], v[88:89]
	s_nop 0
	v_pk_fma_f32 v[94:95], v[90:91], v[16:17], v[94:95]
	s_nop 0
	v_add_f32_e32 v98, v94, v95
	v_pk_mul_f32 v[94:95], v[10:11], v[84:85]
	s_nop 0
	v_pk_fma_f32 v[94:95], v[86:87], v[12:13], v[94:95]
	s_nop 0
	v_add_f32_e32 v99, v94, v95
	v_pk_mul_f32 v[94:95], v[22:23], v[88:89]
	v_pk_mul_f32 v[88:89], v[30:31], v[88:89]
	v_pk_fma_f32 v[94:95], v[90:91], v[24:25], v[94:95]
	v_pk_fma_f32 v[88:89], v[90:91], v[32:33], v[88:89]
	v_add_f32_e32 v100, v94, v95
	v_add_f32_e32 v88, v88, v89
	v_pk_mul_f32 v[94:95], v[18:19], v[84:85]
	v_pk_mul_f32 v[84:85], v[26:27], v[84:85]
	v_pk_fma_f32 v[94:95], v[86:87], v[20:21], v[94:95]
	v_pk_fma_f32 v[84:85], v[86:87], v[28:29], v[84:85]
	v_add_f32_e32 v94, v94, v95
	v_add_f32_e32 v84, v84, v85
	s_waitcnt lgkmcnt(0)
	s_nop 1
	v_permlane16_swap_b32 v96, v100
	v_add_f32_e32 v85, v96, v100
	s_waitcnt lgkmcnt(2)
	s_nop 1
	v_permlane16_swap_b32 v97, v94
	v_add_f32_e32 v86, v97, v94
	s_waitcnt lgkmcnt(1)
	s_nop 1
	v_permlane16_swap_b32 v98, v88
	v_add_f32_e32 v87, v98, v88
	s_waitcnt lgkmcnt(0)
	s_nop 1
	v_permlane16_swap_b32 v99, v84
	v_add_f32_e32 v84, v99, v84
	v_cndmask_b32_e64 v88, v85, v87, s[38:39]
	v_cndmask_b32_e64 v85, v87, v85, s[38:39]
	v_cndmask_b32_e64 v87, v86, v84, s[38:39]
	v_cndmask_b32_e64 v84, v84, v86, s[38:39]
	v_add_f32_dpp v85, v88, v85 row_ror:8 row_mask:0xf bank_mask:0xf bound_ctrl:1
	s_nop 0
	v_add_f32_dpp v84, v87, v84 row_ror:8 row_mask:0xf bank_mask:0xf bound_ctrl:1
	v_cndmask_b32_e64 v86, v85, v84, s[42:43]
	v_cndmask_b32_e64 v84, v84, v85, s[42:43]
	v_mov_b32_e32 v85, v35
	v_mov_b32_e32 v87, v35
	s_nop 0
	v_mov_b32_dpp v85, v86 row_ror:4 row_mask:0xf bank_mask:0xf
	v_mov_b32_dpp v87, v86 row_ror:12 row_mask:0xf bank_mask:0xf
	v_cndmask_b32_e64 v85, v85, v87, s[42:43]
	v_add_f32_e32 v84, v84, v85
	v_mov_b32_e32 v85, 0
	s_nop 0
	v_add_f32_dpp v84, v84, v84 quad_perm:[2,3,0,1] row_mask:0xf bank_mask:0xf bound_ctrl:1
	s_nop 1
	v_mov_b32_dpp v85, v84 quad_perm:[1,0,3,2] row_mask:0xf bank_mask:0xf
	s_and_saveexec_b64 s[2:3], s[44:45]
	s_cbranch_execz .LBB0_1153
	v_add_f32_e32 v84, v84, v85
	v_add_f32_e32 v84, v34, v84
	v_exp_f32_e32 v84, v84
	v_add_u32_e32 v86, 64, v126
	v_add_f32_e32 v85, 1.0, v84
	v_rcp_f32_e32 v85, v85
	s_nop 0
	v_mul_f32_e32 v84, v84, v85
	ds_write2st64_b32 v86, v85, v84 offset1:64
.LBB0_1153:
	s_or_b64 exec, exec, s[2:3]
	s_waitcnt vmcnt(11)
	v_pk_mul_f32 v[84:85], v[6:7], v[80:81]
	s_nop 0
	v_pk_fma_f32 v[84:85], v[82:83], v[8:9], v[84:85]
	s_nop 0
	v_add_f32_e32 v86, v84, v85
	s_waitcnt vmcnt(10)
	v_pk_mul_f32 v[84:85], v[2:3], v[76:77]
	s_nop 0
	v_pk_fma_f32 v[84:85], v[78:79], v[4:5], v[84:85]
	s_nop 0
	v_add_f32_e32 v87, v84, v85
	v_pk_mul_f32 v[84:85], v[14:15], v[80:81]
	s_nop 0
	v_pk_fma_f32 v[84:85], v[82:83], v[16:17], v[84:85]
	s_nop 0
	v_add_f32_e32 v88, v84, v85
	v_pk_mul_f32 v[84:85], v[10:11], v[76:77]
	s_nop 0
	v_pk_fma_f32 v[84:85], v[78:79], v[12:13], v[84:85]
	s_nop 0
	v_add_f32_e32 v89, v84, v85
	v_pk_mul_f32 v[84:85], v[22:23], v[80:81]
	v_pk_mul_f32 v[80:81], v[30:31], v[80:81]
	v_pk_fma_f32 v[84:85], v[82:83], v[24:25], v[84:85]
	v_pk_fma_f32 v[80:81], v[82:83], v[32:33], v[80:81]
	v_add_f32_e32 v90, v84, v85
	v_add_f32_e32 v80, v80, v81
	v_pk_mul_f32 v[84:85], v[18:19], v[76:77]
	v_pk_mul_f32 v[76:77], v[26:27], v[76:77]
	v_pk_fma_f32 v[84:85], v[78:79], v[20:21], v[84:85]
	v_pk_fma_f32 v[76:77], v[78:79], v[28:29], v[76:77]
	v_add_f32_e32 v84, v84, v85
	v_add_f32_e32 v76, v76, v77
	s_waitcnt lgkmcnt(0)
	s_nop 1
	v_permlane16_swap_b32 v86, v90
	v_add_f32_e32 v77, v86, v90
	s_waitcnt lgkmcnt(2)
	s_nop 1
	v_permlane16_swap_b32 v87, v84
	v_add_f32_e32 v78, v87, v84
	s_waitcnt lgkmcnt(1)
	s_nop 1
	v_permlane16_swap_b32 v88, v80
	v_add_f32_e32 v79, v88, v80
	s_waitcnt lgkmcnt(0)
	s_nop 1
	v_permlane16_swap_b32 v89, v76
	v_add_f32_e32 v76, v89, v76
	v_cndmask_b32_e64 v80, v77, v79, s[38:39]
	v_cndmask_b32_e64 v77, v79, v77, s[38:39]
	v_cndmask_b32_e64 v79, v78, v76, s[38:39]
	v_cndmask_b32_e64 v76, v76, v78, s[38:39]
	v_add_f32_dpp v77, v80, v77 row_ror:8 row_mask:0xf bank_mask:0xf bound_ctrl:1
	s_nop 0
	v_add_f32_dpp v76, v79, v76 row_ror:8 row_mask:0xf bank_mask:0xf bound_ctrl:1
	v_cndmask_b32_e64 v78, v77, v76, s[42:43]
	v_cndmask_b32_e64 v76, v76, v77, s[42:43]
	v_mov_b32_e32 v77, v35
	v_mov_b32_e32 v79, v35
	s_nop 0
	v_mov_b32_dpp v77, v78 row_ror:4 row_mask:0xf bank_mask:0xf
	v_mov_b32_dpp v79, v78 row_ror:12 row_mask:0xf bank_mask:0xf
	v_cndmask_b32_e64 v77, v77, v79, s[42:43]
	v_add_f32_e32 v76, v76, v77
	v_mov_b32_e32 v77, 0
	s_nop 0
	v_add_f32_dpp v76, v76, v76 quad_perm:[2,3,0,1] row_mask:0xf bank_mask:0xf bound_ctrl:1
	s_nop 1
	v_mov_b32_dpp v77, v76 quad_perm:[1,0,3,2] row_mask:0xf bank_mask:0xf
	s_and_saveexec_b64 s[2:3], s[44:45]
	s_cbranch_execz .LBB0_1155
	v_add_f32_e32 v76, v76, v77
	v_add_f32_e32 v76, v34, v76
	v_exp_f32_e32 v76, v76
	v_add_u32_e32 v78, 0x80, v126
	v_add_f32_e32 v77, 1.0, v76
	v_rcp_f32_e32 v77, v77
	s_nop 0
	v_mul_f32_e32 v76, v76, v77
	ds_write2st64_b32 v78, v77, v76 offset1:64
.LBB0_1155:
	s_or_b64 exec, exec, s[2:3]
	s_waitcnt vmcnt(9)
	v_pk_mul_f32 v[76:77], v[6:7], v[72:73]
	s_nop 0
	v_pk_fma_f32 v[76:77], v[74:75], v[8:9], v[76:77]
	s_nop 0
	v_add_f32_e32 v78, v76, v77
	s_waitcnt vmcnt(8)
	v_pk_mul_f32 v[76:77], v[2:3], v[68:69]
	s_nop 0
	v_pk_fma_f32 v[76:77], v[70:71], v[4:5], v[76:77]
	s_nop 0
	v_add_f32_e32 v79, v76, v77
	v_pk_mul_f32 v[76:77], v[14:15], v[72:73]
	s_nop 0
	v_pk_fma_f32 v[76:77], v[74:75], v[16:17], v[76:77]
	s_nop 0
	v_add_f32_e32 v80, v76, v77
	v_pk_mul_f32 v[76:77], v[10:11], v[68:69]
	s_nop 0
	v_pk_fma_f32 v[76:77], v[70:71], v[12:13], v[76:77]
	s_nop 0
	v_add_f32_e32 v81, v76, v77
	v_pk_mul_f32 v[76:77], v[22:23], v[72:73]
	v_pk_mul_f32 v[72:73], v[30:31], v[72:73]
	v_pk_fma_f32 v[76:77], v[74:75], v[24:25], v[76:77]
	v_pk_fma_f32 v[72:73], v[74:75], v[32:33], v[72:73]
	v_add_f32_e32 v82, v76, v77
	v_add_f32_e32 v72, v72, v73
	v_pk_mul_f32 v[76:77], v[18:19], v[68:69]
	v_pk_mul_f32 v[68:69], v[26:27], v[68:69]
	v_pk_fma_f32 v[76:77], v[70:71], v[20:21], v[76:77]
	v_pk_fma_f32 v[68:69], v[70:71], v[28:29], v[68:69]
	v_add_f32_e32 v76, v76, v77
	v_add_f32_e32 v68, v68, v69
	s_waitcnt lgkmcnt(0)
	s_nop 1
	v_permlane16_swap_b32 v78, v82
	v_add_f32_e32 v69, v78, v82
	s_waitcnt lgkmcnt(2)
	s_nop 1
	v_permlane16_swap_b32 v79, v76
	v_add_f32_e32 v70, v79, v76
	s_waitcnt lgkmcnt(1)
	s_nop 1
	v_permlane16_swap_b32 v80, v72
	v_add_f32_e32 v71, v80, v72
	s_waitcnt lgkmcnt(0)
	s_nop 1
	v_permlane16_swap_b32 v81, v68
	v_add_f32_e32 v68, v81, v68
	v_cndmask_b32_e64 v72, v69, v71, s[38:39]
	v_cndmask_b32_e64 v69, v71, v69, s[38:39]
	v_cndmask_b32_e64 v71, v70, v68, s[38:39]
	v_cndmask_b32_e64 v68, v68, v70, s[38:39]
	v_add_f32_dpp v69, v72, v69 row_ror:8 row_mask:0xf bank_mask:0xf bound_ctrl:1
	s_nop 0
	v_add_f32_dpp v68, v71, v68 row_ror:8 row_mask:0xf bank_mask:0xf bound_ctrl:1
	v_cndmask_b32_e64 v70, v69, v68, s[42:43]
	v_cndmask_b32_e64 v68, v68, v69, s[42:43]
	v_mov_b32_e32 v69, v35
	v_mov_b32_e32 v71, v35
	s_nop 0
	v_mov_b32_dpp v69, v70 row_ror:4 row_mask:0xf bank_mask:0xf
	v_mov_b32_dpp v71, v70 row_ror:12 row_mask:0xf bank_mask:0xf
	v_cndmask_b32_e64 v69, v69, v71, s[42:43]
	v_add_f32_e32 v68, v68, v69
	v_mov_b32_e32 v69, 0
	s_nop 0
	v_add_f32_dpp v68, v68, v68 quad_perm:[2,3,0,1] row_mask:0xf bank_mask:0xf bound_ctrl:1
	s_nop 1
	v_mov_b32_dpp v69, v68 quad_perm:[1,0,3,2] row_mask:0xf bank_mask:0xf
	s_and_saveexec_b64 s[2:3], s[44:45]
	s_cbranch_execz .LBB0_1157
	v_add_f32_e32 v68, v68, v69
	v_add_f32_e32 v68, v34, v68
	v_exp_f32_e32 v68, v68
	v_add_u32_e32 v70, 0xc0, v126
	v_add_f32_e32 v69, 1.0, v68
	v_rcp_f32_e32 v69, v69
	s_nop 0
	v_mul_f32_e32 v68, v68, v69
	ds_write2st64_b32 v70, v69, v68 offset1:64
; #define DEC_LOADK(dst, i0) do { asm volatile("" ::: "memory"); _Pragma("unroll") for (int u = 0; u < 4; ++u) { const float* kr = ck + rbase + (size_t)((i0) + u) * 512; dst[u][0] = __builtin_nontemporal_load((const f32x4*)(kr + 4 * lane)); dst[u][1] = __builtin_nontemporal_load((const f32x4*)(kr + 256 + 4 * lane)); } } while (0)
; __device__ __forceinline__ void decode_item(Frame& F, const Args& a, int l, int item, unsigned char* ws) {
;     ...
;         DEC_LOADK(ka, 0); DEC_LOADK(kb, 4); DEC_SCORE(ka, 0); DEC_LOADK(ka, 8); DEC_SCORE(kb, 4); DEC_LOADK(kb, 12); DEC_SCORE(ka, 8); DEC_LOADK(ka, 16); DEC_SCORE(kb, 12); DEC_LOADK(kb, 20); DEC_SCORE(ka, 16); DEC_LOADK(ka, 24); DEC_SCORE(kb, 20); DEC_LOADK(kb, 28); DEC_SCORE(ka, 24); DEC_SCORE(kb, 28);
.LBB0_1157:
	s_or_b64 exec, exec, s[2:3]
	v_lshl_add_u64 v[120:121], v[116:117], 2, v[92:93]
	v_add_co_u32_e32 v68, vcc, 0x4000, v120
	s_waitcnt vmcnt(7)
	v_pk_mul_f32 v[84:85], v[6:7], v[64:65]
	v_addc_co_u32_e32 v69, vcc, 0, v121, vcc
	global_load_dwordx4 v[112:115], v[68:69], off nt
	global_load_dwordx4 v[104:107], v[68:69], off offset:1024 nt
	global_load_dwordx4 v[96:99], v[68:69], off offset:2048 nt
	global_load_dwordx4 v[88:91], v[68:69], off offset:3072 nt
	v_add_co_u32_e32 v68, vcc, 0x5000, v120
	v_pk_fma_f32 v[84:85], v[66:67], v[8:9], v[84:85]
	s_nop 0
	v_addc_co_u32_e32 v69, vcc, 0, v121, vcc
	global_load_dwordx4 v[80:83], v[68:69], off nt
	global_load_dwordx4 v[76:79], v[68:69], off offset:1024 nt
	global_load_dwordx4 v[72:75], v[68:69], off offset:2048 nt
	s_nop 0
	global_load_dwordx4 v[68:71], v[68:69], off offset:3072 nt
	v_add_f32_e32 v86, v84, v85
	s_waitcnt vmcnt(14)
	v_pk_mul_f32 v[84:85], v[2:3], v[60:61]
	s_nop 0
	v_pk_fma_f32 v[84:85], v[62:63], v[4:5], v[84:85]
	s_nop 0
	v_add_f32_e32 v87, v84, v85
	v_pk_mul_f32 v[84:85], v[14:15], v[64:65]
	s_nop 0
	v_pk_fma_f32 v[84:85], v[66:67], v[16:17], v[84:85]
	s_nop 0
	v_add_f32_e32 v92, v84, v85
	v_pk_mul_f32 v[84:85], v[10:11], v[60:61]
	s_nop 0
	v_pk_fma_f32 v[84:85], v[62:63], v[12:13], v[84:85]
	s_nop 0
	v_add_f32_e32 v93, v84, v85
	v_pk_mul_f32 v[84:85], v[22:23], v[64:65]
	v_pk_mul_f32 v[64:65], v[30:31], v[64:65]
	v_pk_fma_f32 v[84:85], v[66:67], v[24:25], v[84:85]
	v_pk_fma_f32 v[64:65], v[66:67], v[32:33], v[64:65]
	v_add_f32_e32 v94, v84, v85
	v_add_f32_e32 v64, v64, v65
	v_pk_mul_f32 v[84:85], v[18:19], v[60:61]
	v_pk_mul_f32 v[60:61], v[26:27], v[60:61]
	v_pk_fma_f32 v[84:85], v[62:63], v[20:21], v[84:85]
	v_pk_fma_f32 v[60:61], v[62:63], v[28:29], v[60:61]
	v_add_f32_e32 v84, v84, v85
	v_add_f32_e32 v60, v60, v61
	s_waitcnt lgkmcnt(0)
	s_nop 1
	v_permlane16_swap_b32 v86, v94
	v_add_f32_e32 v61, v86, v94
	s_waitcnt lgkmcnt(2)
	s_nop 1
	v_permlane16_swap_b32 v87, v84
	v_add_f32_e32 v62, v87, v84
	s_waitcnt lgkmcnt(1)
	s_nop 1
	v_permlane16_swap_b32 v92, v64
	v_add_f32_e32 v63, v92, v64
	s_waitcnt lgkmcnt(0)
	s_nop 1
	v_permlane16_swap_b32 v93, v60
	v_add_f32_e32 v60, v93, v60
	v_cndmask_b32_e64 v64, v61, v63, s[38:39]
	v_cndmask_b32_e64 v61, v63, v61, s[38:39]
	v_cndmask_b32_e64 v63, v62, v60, s[38:39]
	v_cndmask_b32_e64 v60, v60, v62, s[38:39]
	v_add_f32_dpp v61, v64, v61 row_ror:8 row_mask:0xf bank_mask:0xf bound_ctrl:1
	s_nop 0
	v_add_f32_dpp v60, v63, v60 row_ror:8 row_mask:0xf bank_mask:0xf bound_ctrl:1
	v_cndmask_b32_e64 v62, v61, v60, s[42:43]
	v_cndmask_b32_e64 v60, v60, v61, s[42:43]
	v_mov_b32_e32 v61, v35
	v_mov_b32_e32 v63, v35
	s_nop 0
	v_mov_b32_dpp v61, v62 row_ror:4 row_mask:0xf bank_mask:0xf
	v_mov_b32_dpp v63, v62 row_ror:12 row_mask:0xf bank_mask:0xf
	v_cndmask_b32_e64 v61, v61, v63, s[42:43]
	v_add_f32_e32 v60, v60, v61
	v_mov_b32_e32 v61, 0
	s_nop 0
	v_add_f32_dpp v60, v60, v60 quad_perm:[2,3,0,1] row_mask:0xf bank_mask:0xf bound_ctrl:1
	s_nop 1
	v_mov_b32_dpp v61, v60 quad_perm:[1,0,3,2] row_mask:0xf bank_mask:0xf
	s_and_saveexec_b64 s[2:3], s[44:45]
	s_cbranch_execz .LBB0_1159
	v_add_f32_e32 v60, v60, v61
	v_add_f32_e32 v60, v34, v60
	v_exp_f32_e32 v60, v60
	s_nop 0
	v_add_f32_e32 v61, 1.0, v60
	v_rcp_f32_e32 v61, v61
	s_nop 0
	v_mul_f32_e32 v60, v60, v61
	ds_write2st64_b32 v126, v61, v60 offset0:1 offset1:65
.LBB0_1159:
	s_or_b64 exec, exec, s[2:3]
	s_waitcnt vmcnt(13)
	v_pk_mul_f32 v[60:61], v[6:7], v[52:53]
	s_nop 0
	v_pk_fma_f32 v[60:61], v[54:55], v[8:9], v[60:61]
	s_nop 0
	v_add_f32_e32 v62, v60, v61
	s_waitcnt vmcnt(12)
	v_pk_mul_f32 v[60:61], v[2:3], v[44:45]
	s_nop 0
	v_pk_fma_f32 v[60:61], v[46:47], v[4:5], v[60:61]
	s_nop 0
	v_add_f32_e32 v63, v60, v61
	v_pk_mul_f32 v[60:61], v[14:15], v[52:53]
	s_nop 0
	v_pk_fma_f32 v[60:61], v[54:55], v[16:17], v[60:61]
	s_nop 0
	v_add_f32_e32 v64, v60, v61
	v_pk_mul_f32 v[60:61], v[10:11], v[44:45]
	s_nop 0
	v_pk_fma_f32 v[60:61], v[46:47], v[12:13], v[60:61]
	s_nop 0
	v_add_f32_e32 v65, v60, v61
	v_pk_mul_f32 v[60:61], v[22:23], v[52:53]
	v_pk_mul_f32 v[52:53], v[30:31], v[52:53]
	v_pk_fma_f32 v[60:61], v[54:55], v[24:25], v[60:61]
	v_pk_fma_f32 v[52:53], v[54:55], v[32:33], v[52:53]
	v_add_f32_e32 v66, v60, v61
	v_add_f32_e32 v52, v52, v53
	v_pk_mul_f32 v[60:61], v[18:19], v[44:45]
	v_pk_mul_f32 v[44:45], v[26:27], v[44:45]
	v_pk_fma_f32 v[60:61], v[46:47], v[20:21], v[60:61]
	v_pk_fma_f32 v[44:45], v[46:47], v[28:29], v[44:45]
	v_add_f32_e32 v60, v60, v61
	v_add_f32_e32 v44, v44, v45
	s_waitcnt lgkmcnt(0)
	s_nop 1
	v_permlane16_swap_b32 v62, v66
	v_add_f32_e32 v45, v62, v66
	s_waitcnt lgkmcnt(2)
	s_nop 1
	v_permlane16_swap_b32 v63, v60
	v_add_f32_e32 v46, v63, v60
	s_waitcnt lgkmcnt(1)
	s_nop 1
	v_permlane16_swap_b32 v64, v52
	v_add_f32_e32 v47, v64, v52
	s_waitcnt lgkmcnt(0)
	s_nop 1
	v_permlane16_swap_b32 v65, v44
	v_add_f32_e32 v44, v65, v44
	v_cndmask_b32_e64 v52, v45, v47, s[38:39]
	v_cndmask_b32_e64 v45, v47, v45, s[38:39]
	v_cndmask_b32_e64 v47, v46, v44, s[38:39]
	v_cndmask_b32_e64 v44, v44, v46, s[38:39]
	v_add_f32_dpp v45, v52, v45 row_ror:8 row_mask:0xf bank_mask:0xf bound_ctrl:1
	s_nop 0
	v_add_f32_dpp v44, v47, v44 row_ror:8 row_mask:0xf bank_mask:0xf bound_ctrl:1
	v_cndmask_b32_e64 v46, v45, v44, s[42:43]
	v_cndmask_b32_e64 v44, v44, v45, s[42:43]
	v_mov_b32_e32 v45, v35
	v_mov_b32_e32 v47, v35
	s_nop 0
	v_mov_b32_dpp v45, v46 row_ror:4 row_mask:0xf bank_mask:0xf
	v_mov_b32_dpp v47, v46 row_ror:12 row_mask:0xf bank_mask:0xf
	v_cndmask_b32_e64 v45, v45, v47, s[42:43]
	v_add_f32_e32 v44, v44, v45
	v_mov_b32_e32 v45, 0
	s_nop 0
	v_add_f32_dpp v44, v44, v44 quad_perm:[2,3,0,1] row_mask:0xf bank_mask:0xf bound_ctrl:1
	s_nop 1
	v_mov_b32_dpp v45, v44 quad_perm:[1,0,3,2] row_mask:0xf bank_mask:0xf
	s_and_saveexec_b64 s[2:3], s[44:45]
	s_cbranch_execz .LBB0_1161
	v_add_f32_e32 v44, v44, v45
	v_add_f32_e32 v44, v34, v44
	v_exp_f32_e32 v44, v44
	v_add_u32_e32 v46, 64, v126
	v_add_f32_e32 v45, 1.0, v44
	v_rcp_f32_e32 v45, v45
	s_nop 0
	v_mul_f32_e32 v44, v44, v45
	ds_write2st64_b32 v46, v45, v44 offset0:1 offset1:65

.LBB0_1163:
	s_or_b64 exec, exec, s[2:3]
	s_waitcnt vmcnt(9)
	v_pk_mul_f32 v[44:45], v[6:7], v[40:41]
	s_nop 0
	v_pk_fma_f32 v[44:45], v[42:43], v[8:9], v[44:45]
	s_nop 0
	v_add_f32_e32 v46, v44, v45
	s_waitcnt vmcnt(8)
	v_pk_mul_f32 v[44:45], v[2:3], v[36:37]
	s_nop 0
	v_pk_fma_f32 v[44:45], v[38:39], v[4:5], v[44:45]
	s_nop 0
	v_add_f32_e32 v47, v44, v45
	v_pk_mul_f32 v[44:45], v[14:15], v[40:41]
	s_nop 0
	v_pk_fma_f32 v[44:45], v[42:43], v[16:17], v[44:45]
	s_nop 0
	v_add_f32_e32 v48, v44, v45
	v_pk_mul_f32 v[44:45], v[10:11], v[36:37]
	s_nop 0
	v_pk_fma_f32 v[44:45], v[38:39], v[12:13], v[44:45]
	s_nop 0
	v_add_f32_e32 v49, v44, v45
	v_pk_mul_f32 v[44:45], v[22:23], v[40:41]
	v_pk_mul_f32 v[40:41], v[30:31], v[40:41]
	v_pk_fma_f32 v[44:45], v[42:43], v[24:25], v[44:45]
	v_pk_fma_f32 v[40:41], v[42:43], v[32:33], v[40:41]
	v_add_f32_e32 v50, v44, v45
	v_add_f32_e32 v40, v40, v41
	v_pk_mul_f32 v[44:45], v[18:19], v[36:37]
	v_pk_mul_f32 v[36:37], v[26:27], v[36:37]
	v_pk_fma_f32 v[44:45], v[38:39], v[20:21], v[44:45]
	v_pk_fma_f32 v[36:37], v[38:39], v[28:29], v[36:37]
	v_add_f32_e32 v44, v44, v45
	v_add_f32_e32 v36, v36, v37
	s_waitcnt lgkmcnt(0)
	s_nop 1
	v_permlane16_swap_b32 v46, v50
	v_add_f32_e32 v37, v46, v50
	s_waitcnt lgkmcnt(2)
	s_nop 1
	v_permlane16_swap_b32 v47, v44
	v_add_f32_e32 v38, v47, v44
	s_waitcnt lgkmcnt(1)
	s_nop 1
	v_permlane16_swap_b32 v48, v40
	v_add_f32_e32 v39, v48, v40
	s_waitcnt lgkmcnt(0)
	s_nop 1
	v_permlane16_swap_b32 v49, v36
	v_add_f32_e32 v36, v49, v36
	v_cndmask_b32_e64 v40, v37, v39, s[38:39]
	v_cndmask_b32_e64 v37, v39, v37, s[38:39]
	v_cndmask_b32_e64 v39, v38, v36, s[38:39]
	v_cndmask_b32_e64 v36, v36, v38, s[38:39]
	v_add_f32_dpp v37, v40, v37 row_ror:8 row_mask:0xf bank_mask:0xf bound_ctrl:1
	s_nop 0
	v_add_f32_dpp v36, v39, v36 row_ror:8 row_mask:0xf bank_mask:0xf bound_ctrl:1
	v_cndmask_b32_e64 v38, v37, v36, s[42:43]
	v_cndmask_b32_e64 v36, v36, v37, s[42:43]
	v_mov_b32_e32 v37, v35
	v_mov_b32_e32 v39, v35
	s_nop 0
	v_mov_b32_dpp v37, v38 row_ror:4 row_mask:0xf bank_mask:0xf
	v_mov_b32_dpp v39, v38 row_ror:12 row_mask:0xf bank_mask:0xf
	v_cndmask_b32_e64 v37, v37, v39, s[42:43]
	v_add_f32_e32 v36, v36, v37
	v_mov_b32_e32 v37, 0
	s_nop 0
	v_add_f32_dpp v36, v36, v36 quad_perm:[2,3,0,1] row_mask:0xf bank_mask:0xf bound_ctrl:1
	s_nop 1
	v_mov_b32_dpp v37, v36 quad_perm:[1,0,3,2] row_mask:0xf bank_mask:0xf
	s_and_saveexec_b64 s[2:3], s[44:45]
	s_cbranch_execz .LBB0_1165
	v_add_f32_e32 v36, v36, v37
	v_add_f32_e32 v36, v34, v36
	v_exp_f32_e32 v36, v36
	v_add_u32_e32 v38, 0xc0, v126
	v_add_f32_e32 v37, 1.0, v36
	v_rcp_f32_e32 v37, v37
	s_nop 0
	v_mul_f32_e32 v36, v36, v37
	ds_write2st64_b32 v38, v37, v36 offset0:1 offset1:65

.LBB0_1177:
	s_or_b64 exec, exec, s[2:3]
	s_waitcnt vmcnt(11)
	v_pk_mul_f32 v[72:73], v[6:7], v[60:61]
	s_nop 0
	v_pk_fma_f32 v[72:73], v[62:63], v[8:9], v[72:73]
	s_nop 0
	v_add_f32_e32 v74, v72, v73
	s_waitcnt vmcnt(10)
	v_pk_mul_f32 v[72:73], v[2:3], v[52:53]
	s_nop 0
	v_pk_fma_f32 v[72:73], v[54:55], v[4:5], v[72:73]
	s_nop 0
	v_add_f32_e32 v75, v72, v73
	v_pk_mul_f32 v[72:73], v[14:15], v[60:61]
	s_nop 0
	v_pk_fma_f32 v[72:73], v[62:63], v[16:17], v[72:73]
	s_nop 0
	v_add_f32_e32 v80, v72, v73
	v_pk_mul_f32 v[72:73], v[10:11], v[52:53]
	s_nop 0
	v_pk_fma_f32 v[72:73], v[54:55], v[12:13], v[72:73]
	s_nop 0
	v_add_f32_e32 v81, v72, v73
	v_pk_mul_f32 v[72:73], v[22:23], v[60:61]
	v_pk_mul_f32 v[60:61], v[30:31], v[60:61]
	v_pk_fma_f32 v[72:73], v[62:63], v[24:25], v[72:73]
	v_pk_fma_f32 v[60:61], v[62:63], v[32:33], v[60:61]
	v_add_f32_e32 v82, v72, v73
	v_add_f32_e32 v60, v60, v61
	v_pk_mul_f32 v[72:73], v[18:19], v[52:53]
	v_pk_mul_f32 v[52:53], v[26:27], v[52:53]
	v_pk_fma_f32 v[72:73], v[54:55], v[20:21], v[72:73]
	v_pk_fma_f32 v[52:53], v[54:55], v[28:29], v[52:53]
	v_add_f32_e32 v72, v72, v73
	v_add_f32_e32 v52, v52, v53
	s_waitcnt lgkmcnt(0)
	s_nop 1
	v_permlane16_swap_b32 v74, v82
	v_add_f32_e32 v53, v74, v82
	s_waitcnt lgkmcnt(2)
	s_nop 1
	v_permlane16_swap_b32 v75, v72
	v_add_f32_e32 v54, v75, v72
	s_waitcnt lgkmcnt(1)
	s_nop 1
	v_permlane16_swap_b32 v80, v60
	v_add_f32_e32 v55, v80, v60
	s_waitcnt lgkmcnt(0)
	s_nop 1
	v_permlane16_swap_b32 v81, v52
	v_add_f32_e32 v52, v81, v52
	v_cndmask_b32_e64 v60, v53, v55, s[38:39]
	v_cndmask_b32_e64 v53, v55, v53, s[38:39]
	v_cndmask_b32_e64 v55, v54, v52, s[38:39]
	v_cndmask_b32_e64 v52, v52, v54, s[38:39]
	v_add_f32_dpp v53, v60, v53 row_ror:8 row_mask:0xf bank_mask:0xf bound_ctrl:1
	s_nop 0
	v_add_f32_dpp v52, v55, v52 row_ror:8 row_mask:0xf bank_mask:0xf bound_ctrl:1
	v_cndmask_b32_e64 v54, v53, v52, s[42:43]
	v_cndmask_b32_e64 v52, v52, v53, s[42:43]
	v_mov_b32_e32 v53, v35
	v_mov_b32_e32 v55, v35
	s_nop 0
	v_mov_b32_dpp v53, v54 row_ror:4 row_mask:0xf bank_mask:0xf
	v_mov_b32_dpp v55, v54 row_ror:12 row_mask:0xf bank_mask:0xf
	v_cndmask_b32_e64 v53, v53, v55, s[42:43]
	v_add_f32_e32 v52, v52, v53
	v_mov_b32_e32 v53, 0
	s_nop 0
	v_add_f32_dpp v52, v52, v52 quad_perm:[2,3,0,1] row_mask:0xf bank_mask:0xf bound_ctrl:1
	s_nop 1
	v_mov_b32_dpp v53, v52 quad_perm:[1,0,3,2] row_mask:0xf bank_mask:0xf
	s_and_saveexec_b64 s[2:3], s[44:45]
	s_cbranch_execz .LBB0_1179
	v_add_f32_e32 v52, v52, v53
	v_add_f32_e32 v52, v34, v52
	v_exp_f32_e32 v52, v52
	v_add_u32_e32 v54, 0x80, v126
	v_add_f32_e32 v53, 1.0, v52
	v_rcp_f32_e32 v53, v53
	s_nop 0
	v_mul_f32_e32 v52, v52, v53
	ds_write2st64_b32 v54, v53, v52 offset0:3 offset1:67
.LBB0_1179:
	s_or_b64 exec, exec, s[2:3]
	s_waitcnt vmcnt(9)
	v_pk_mul_f32 v[52:53], v[6:7], v[44:45]
	s_nop 0
	v_pk_fma_f32 v[52:53], v[46:47], v[8:9], v[52:53]
	s_nop 0
	v_add_f32_e32 v54, v52, v53
	s_waitcnt vmcnt(8)
	v_pk_mul_f32 v[52:53], v[2:3], v[36:37]
	s_nop 0
	v_pk_fma_f32 v[52:53], v[38:39], v[4:5], v[52:53]
	s_nop 0
	v_add_f32_e32 v55, v52, v53
	v_pk_mul_f32 v[52:53], v[14:15], v[44:45]
	s_nop 0
	v_pk_fma_f32 v[52:53], v[46:47], v[16:17], v[52:53]
	s_nop 0
	v_add_f32_e32 v60, v52, v53
	v_pk_mul_f32 v[52:53], v[10:11], v[36:37]
	s_nop 0
	v_pk_fma_f32 v[52:53], v[38:39], v[12:13], v[52:53]
	s_nop 0
	v_add_f32_e32 v61, v52, v53
	v_pk_mul_f32 v[52:53], v[22:23], v[44:45]
	v_pk_mul_f32 v[44:45], v[30:31], v[44:45]
	v_pk_fma_f32 v[52:53], v[46:47], v[24:25], v[52:53]
	v_pk_fma_f32 v[44:45], v[46:47], v[32:33], v[44:45]
	v_add_f32_e32 v62, v52, v53
	v_add_f32_e32 v44, v44, v45
	v_pk_mul_f32 v[52:53], v[18:19], v[36:37]
	v_pk_mul_f32 v[36:37], v[26:27], v[36:37]
	v_pk_fma_f32 v[52:53], v[38:39], v[20:21], v[52:53]
	v_pk_fma_f32 v[36:37], v[38:39], v[28:29], v[36:37]
	v_add_f32_e32 v52, v52, v53
	v_add_f32_e32 v36, v36, v37
	s_waitcnt lgkmcnt(0)
	s_nop 1
	v_permlane16_swap_b32 v54, v62
	v_add_f32_e32 v37, v54, v62
	s_waitcnt lgkmcnt(2)
	s_nop 1
	v_permlane16_swap_b32 v55, v52
	v_add_f32_e32 v38, v55, v52
	s_waitcnt lgkmcnt(1)
	s_nop 1
	v_permlane16_swap_b32 v60, v44
	v_add_f32_e32 v39, v60, v44
	s_waitcnt lgkmcnt(0)
	s_nop 1
	v_permlane16_swap_b32 v61, v36
	v_add_f32_e32 v36, v61, v36
	v_cndmask_b32_e64 v44, v37, v39, s[38:39]
	v_cndmask_b32_e64 v37, v39, v37, s[38:39]
	v_cndmask_b32_e64 v39, v38, v36, s[38:39]
	v_cndmask_b32_e64 v36, v36, v38, s[38:39]
	v_add_f32_dpp v37, v44, v37 row_ror:8 row_mask:0xf bank_mask:0xf bound_ctrl:1
	s_nop 0
	v_add_f32_dpp v36, v39, v36 row_ror:8 row_mask:0xf bank_mask:0xf bound_ctrl:1
	v_cndmask_b32_e64 v38, v37, v36, s[42:43]
	v_cndmask_b32_e64 v36, v36, v37, s[42:43]
	v_mov_b32_e32 v37, v35
	v_mov_b32_e32 v39, v35
	s_nop 0
	v_mov_b32_dpp v37, v38 row_ror:4 row_mask:0xf bank_mask:0xf
	v_mov_b32_dpp v39, v38 row_ror:12 row_mask:0xf bank_mask:0xf
	v_cndmask_b32_e64 v37, v37, v39, s[42:43]
	v_add_f32_e32 v36, v36, v37
	v_mov_b32_e32 v37, 0
	s_nop 0
	v_add_f32_dpp v36, v36, v36 quad_perm:[2,3,0,1] row_mask:0xf bank_mask:0xf bound_ctrl:1
	s_nop 1
	v_mov_b32_dpp v37, v36 quad_perm:[1,0,3,2] row_mask:0xf bank_mask:0xf
	s_and_saveexec_b64 s[2:3], s[44:45]
	s_cbranch_execz .LBB0_1181
	v_add_f32_e32 v36, v36, v37
	v_add_f32_e32 v36, v34, v36
	v_exp_f32_e32 v36, v36
	v_add_u32_e32 v38, 0xc0, v126
	v_add_f32_e32 v37, 1.0, v36
	v_rcp_f32_e32 v37, v37
	s_nop 0
	v_mul_f32_e32 v36, v36, v37
	ds_write2st64_b32 v38, v37, v36 offset0:3 offset1:67
; #define DEC_LOADK(dst, i0) do { asm volatile("" ::: "memory"); _Pragma("unroll") for (int u = 0; u < 4; ++u) { const float* kr = ck + rbase + (size_t)((i0) + u) * 512; dst[u][0] = __builtin_nontemporal_load((const f32x4*)(kr + 4 * lane)); dst[u][1] = __builtin_nontemporal_load((const f32x4*)(kr + 256 + 4 * lane)); } } while (0)
; __device__ __forceinline__ void decode_item(Frame& F, const Args& a, int l, int item, unsigned char* ws) {
;     ...
;         DEC_LOADK(ka, 0); DEC_LOADK(kb, 4); DEC_SCORE(ka, 0); DEC_LOADK(ka, 8); DEC_SCORE(kb, 4); DEC_LOADK(kb, 12); DEC_SCORE(ka, 8); DEC_LOADK(ka, 16); DEC_SCORE(kb, 12); DEC_LOADK(kb, 20); DEC_SCORE(ka, 16); DEC_LOADK(ka, 24); DEC_SCORE(kb, 20); DEC_LOADK(kb, 28); DEC_SCORE(ka, 24); DEC_SCORE(kb, 28);
.LBB0_1181:
	s_or_b64 exec, exec, s[2:3]
	v_add_co_u32_e32 v36, vcc, 0xa000, v120
	s_waitcnt vmcnt(7)
	v_pk_mul_f32 v[100:101], v[6:7], v[96:97]
	v_addc_co_u32_e32 v37, vcc, 0, v121, vcc
	global_load_dwordx4 v[92:95], v[36:37], off nt
	global_load_dwordx4 v[84:87], v[36:37], off offset:1024 nt
	global_load_dwordx4 v[80:83], v[36:37], off offset:2048 nt
	global_load_dwordx4 v[72:75], v[36:37], off offset:3072 nt
	v_add_co_u32_e32 v36, vcc, 0xb000, v120
	v_pk_fma_f32 v[100:101], v[98:99], v[8:9], v[100:101]
	s_nop 0
	v_addc_co_u32_e32 v37, vcc, 0, v121, vcc
	global_load_dwordx4 v[60:63], v[36:37], off nt
	global_load_dwordx4 v[52:55], v[36:37], off offset:1024 nt
	global_load_dwordx4 v[44:47], v[36:37], off offset:2048 nt
	s_nop 0
	global_load_dwordx4 v[36:39], v[36:37], off offset:3072 nt
	v_add_f32_e32 v102, v100, v101
	s_waitcnt vmcnt(14)
	v_pk_mul_f32 v[100:101], v[2:3], v[88:89]
	s_nop 0
	v_pk_fma_f32 v[100:101], v[90:91], v[4:5], v[100:101]
	s_nop 0
	v_add_f32_e32 v103, v100, v101
	v_pk_mul_f32 v[100:101], v[14:15], v[96:97]
	s_nop 0
	v_pk_fma_f32 v[100:101], v[98:99], v[16:17], v[100:101]
	s_nop 0
	v_add_f32_e32 v104, v100, v101
	v_pk_mul_f32 v[100:101], v[10:11], v[88:89]
	s_nop 0
	v_pk_fma_f32 v[100:101], v[90:91], v[12:13], v[100:101]
	s_nop 0
	v_add_f32_e32 v105, v100, v101
	v_pk_mul_f32 v[100:101], v[22:23], v[96:97]
	v_pk_mul_f32 v[96:97], v[30:31], v[96:97]
	v_pk_fma_f32 v[100:101], v[98:99], v[24:25], v[100:101]
	v_pk_fma_f32 v[96:97], v[98:99], v[32:33], v[96:97]
	v_add_f32_e32 v106, v100, v101
	v_add_f32_e32 v96, v96, v97
	v_pk_mul_f32 v[100:101], v[18:19], v[88:89]
	v_pk_mul_f32 v[88:89], v[26:27], v[88:89]
	v_pk_fma_f32 v[100:101], v[90:91], v[20:21], v[100:101]
	v_pk_fma_f32 v[88:89], v[90:91], v[28:29], v[88:89]
	v_add_f32_e32 v100, v100, v101
	v_add_f32_e32 v88, v88, v89
	s_waitcnt lgkmcnt(0)
	s_nop 1
	v_permlane16_swap_b32 v102, v106
	v_add_f32_e32 v89, v102, v106
	s_waitcnt lgkmcnt(2)
	s_nop 1
	v_permlane16_swap_b32 v103, v100
	v_add_f32_e32 v90, v103, v100
	s_waitcnt lgkmcnt(1)
	s_nop 1
	v_permlane16_swap_b32 v104, v96
	v_add_f32_e32 v91, v104, v96
	s_waitcnt lgkmcnt(0)
	s_nop 1
	v_permlane16_swap_b32 v105, v88
	v_add_f32_e32 v88, v105, v88
	v_cndmask_b32_e64 v96, v89, v91, s[38:39]
	v_cndmask_b32_e64 v89, v91, v89, s[38:39]
	v_cndmask_b32_e64 v91, v90, v88, s[38:39]
	v_cndmask_b32_e64 v88, v88, v90, s[38:39]
	v_add_f32_dpp v89, v96, v89 row_ror:8 row_mask:0xf bank_mask:0xf bound_ctrl:1
	s_nop 0
	v_add_f32_dpp v88, v91, v88 row_ror:8 row_mask:0xf bank_mask:0xf bound_ctrl:1
	v_cndmask_b32_e64 v90, v89, v88, s[42:43]
	v_cndmask_b32_e64 v88, v88, v89, s[42:43]
	v_mov_b32_e32 v89, v35
	v_mov_b32_e32 v91, v35
	s_nop 0
	v_mov_b32_dpp v89, v90 row_ror:4 row_mask:0xf bank_mask:0xf
	v_mov_b32_dpp v91, v90 row_ror:12 row_mask:0xf bank_mask:0xf
	v_cndmask_b32_e64 v89, v89, v91, s[42:43]
	v_add_f32_e32 v88, v88, v89
	v_mov_b32_e32 v89, 0
	s_nop 0
	v_add_f32_dpp v88, v88, v88 quad_perm:[2,3,0,1] row_mask:0xf bank_mask:0xf bound_ctrl:1
	s_nop 1
	v_mov_b32_dpp v89, v88 quad_perm:[1,0,3,2] row_mask:0xf bank_mask:0xf
	s_and_saveexec_b64 s[2:3], s[44:45]
	s_cbranch_execz .LBB0_1183
	v_add_f32_e32 v88, v88, v89
	v_add_f32_e32 v88, v34, v88
	v_exp_f32_e32 v88, v88
	s_nop 0
	v_add_f32_e32 v89, 1.0, v88
	v_rcp_f32_e32 v89, v89
	s_nop 0
	v_mul_f32_e32 v88, v88, v89
	ds_write2st64_b32 v126, v89, v88 offset0:4 offset1:68
.LBB0_1183:
	s_or_b64 exec, exec, s[2:3]
	s_waitcnt vmcnt(13)
	v_pk_mul_f32 v[88:89], v[6:7], v[76:77]
	s_nop 0
	v_pk_fma_f32 v[88:89], v[78:79], v[8:9], v[88:89]
	s_nop 0
	v_add_f32_e32 v90, v88, v89
	s_waitcnt vmcnt(12)
	v_pk_mul_f32 v[88:89], v[2:3], v[68:69]
	s_nop 0
	v_pk_fma_f32 v[88:89], v[70:71], v[4:5], v[88:89]
	s_nop 0
	v_add_f32_e32 v91, v88, v89
	v_pk_mul_f32 v[88:89], v[14:15], v[76:77]
	s_nop 0
	v_pk_fma_f32 v[88:89], v[78:79], v[16:17], v[88:89]
	s_nop 0
	v_add_f32_e32 v96, v88, v89
	v_pk_mul_f32 v[88:89], v[10:11], v[68:69]
	s_nop 0
	v_pk_fma_f32 v[88:89], v[70:71], v[12:13], v[88:89]
	s_nop 0
	v_add_f32_e32 v97, v88, v89
	v_pk_mul_f32 v[88:89], v[22:23], v[76:77]
	v_pk_mul_f32 v[76:77], v[30:31], v[76:77]
	v_pk_fma_f32 v[88:89], v[78:79], v[24:25], v[88:89]
	v_pk_fma_f32 v[76:77], v[78:79], v[32:33], v[76:77]
	v_add_f32_e32 v98, v88, v89
	v_add_f32_e32 v76, v76, v77
	v_pk_mul_f32 v[88:89], v[18:19], v[68:69]
	v_pk_mul_f32 v[68:69], v[26:27], v[68:69]
	v_pk_fma_f32 v[88:89], v[70:71], v[20:21], v[88:89]
	v_pk_fma_f32 v[68:69], v[70:71], v[28:29], v[68:69]
	v_add_f32_e32 v88, v88, v89
	v_add_f32_e32 v68, v68, v69
	s_waitcnt lgkmcnt(0)
	s_nop 1
	v_permlane16_swap_b32 v90, v98
	v_add_f32_e32 v69, v90, v98
	s_waitcnt lgkmcnt(2)
	s_nop 1
	v_permlane16_swap_b32 v91, v88
	v_add_f32_e32 v70, v91, v88
	s_waitcnt lgkmcnt(1)
	s_nop 1
	v_permlane16_swap_b32 v96, v76
	v_add_f32_e32 v71, v96, v76
	s_waitcnt lgkmcnt(0)
	s_nop 1
	v_permlane16_swap_b32 v97, v68
	v_add_f32_e32 v68, v97, v68
	v_cndmask_b32_e64 v76, v69, v71, s[38:39]
	v_cndmask_b32_e64 v69, v71, v69, s[38:39]
	v_cndmask_b32_e64 v71, v70, v68, s[38:39]
	v_cndmask_b32_e64 v68, v68, v70, s[38:39]
	v_add_f32_dpp v69, v76, v69 row_ror:8 row_mask:0xf bank_mask:0xf bound_ctrl:1
	s_nop 0
	v_add_f32_dpp v68, v71, v68 row_ror:8 row_mask:0xf bank_mask:0xf bound_ctrl:1
	v_cndmask_b32_e64 v70, v69, v68, s[42:43]
	v_cndmask_b32_e64 v68, v68, v69, s[42:43]
	v_mov_b32_e32 v69, v35
	v_mov_b32_e32 v71, v35
	s_nop 0
	v_mov_b32_dpp v69, v70 row_ror:4 row_mask:0xf bank_mask:0xf
	v_mov_b32_dpp v71, v70 row_ror:12 row_mask:0xf bank_mask:0xf
	v_cndmask_b32_e64 v69, v69, v71, s[42:43]
	v_add_f32_e32 v68, v68, v69
	v_mov_b32_e32 v69, 0
	s_nop 0
	v_add_f32_dpp v68, v68, v68 quad_perm:[2,3,0,1] row_mask:0xf bank_mask:0xf bound_ctrl:1
	s_nop 1
	v_mov_b32_dpp v69, v68 quad_perm:[1,0,3,2] row_mask:0xf bank_mask:0xf
	s_and_saveexec_b64 s[2:3], s[44:45]
	s_cbranch_execz .LBB0_1185
	v_add_f32_e32 v68, v68, v69
	v_add_f32_e32 v68, v34, v68
	v_exp_f32_e32 v68, v68
	v_add_u32_e32 v70, 64, v126
	v_add_f32_e32 v69, 1.0, v68
	v_rcp_f32_e32 v69, v69
	s_nop 0
	v_mul_f32_e32 v68, v68, v69
	ds_write2st64_b32 v70, v69, v68 offset0:4 offset1:68
.LBB0_1185:
	s_or_b64 exec, exec, s[2:3]
	s_waitcnt vmcnt(11)
	v_pk_mul_f32 v[68:69], v[6:7], v[64:65]
	s_nop 0
	v_pk_fma_f32 v[68:69], v[66:67], v[8:9], v[68:69]
	s_nop 0
	v_add_f32_e32 v70, v68, v69
	s_waitcnt vmcnt(10)
	v_pk_mul_f32 v[68:69], v[2:3], v[56:57]
	s_nop 0
	v_pk_fma_f32 v[68:69], v[58:59], v[4:5], v[68:69]
	s_nop 0
	v_add_f32_e32 v71, v68, v69
	v_pk_mul_f32 v[68:69], v[14:15], v[64:65]
	s_nop 0
	v_pk_fma_f32 v[68:69], v[66:67], v[16:17], v[68:69]
	s_nop 0
	v_add_f32_e32 v76, v68, v69
	v_pk_mul_f32 v[68:69], v[10:11], v[56:57]
	s_nop 0
	v_pk_fma_f32 v[68:69], v[58:59], v[12:13], v[68:69]
	s_nop 0
	v_add_f32_e32 v77, v68, v69
	v_pk_mul_f32 v[68:69], v[22:23], v[64:65]
	v_pk_mul_f32 v[64:65], v[30:31], v[64:65]
	v_pk_fma_f32 v[68:69], v[66:67], v[24:25], v[68:69]
	v_pk_fma_f32 v[64:65], v[66:67], v[32:33], v[64:65]
	v_add_f32_e32 v78, v68, v69
	v_add_f32_e32 v64, v64, v65
	v_pk_mul_f32 v[68:69], v[18:19], v[56:57]
	v_pk_mul_f32 v[56:57], v[26:27], v[56:57]
	v_pk_fma_f32 v[68:69], v[58:59], v[20:21], v[68:69]
	v_pk_fma_f32 v[56:57], v[58:59], v[28:29], v[56:57]
	v_add_f32_e32 v68, v68, v69
	v_add_f32_e32 v56, v56, v57
	s_waitcnt lgkmcnt(0)
	s_nop 1
	v_permlane16_swap_b32 v70, v78
	v_add_f32_e32 v57, v70, v78
	s_waitcnt lgkmcnt(2)
	s_nop 1
	v_permlane16_swap_b32 v71, v68
	v_add_f32_e32 v58, v71, v68
	s_waitcnt lgkmcnt(1)
	s_nop 1
	v_permlane16_swap_b32 v76, v64
	v_add_f32_e32 v59, v76, v64
	s_waitcnt lgkmcnt(0)
	s_nop 1
	v_permlane16_swap_b32 v77, v56
	v_add_f32_e32 v56, v77, v56
	v_cndmask_b32_e64 v64, v57, v59, s[38:39]
	v_cndmask_b32_e64 v57, v59, v57, s[38:39]
	v_cndmask_b32_e64 v59, v58, v56, s[38:39]
	v_cndmask_b32_e64 v56, v56, v58, s[38:39]
	v_add_f32_dpp v57, v64, v57 row_ror:8 row_mask:0xf bank_mask:0xf bound_ctrl:1
	s_nop 0
	v_add_f32_dpp v56, v59, v56 row_ror:8 row_mask:0xf bank_mask:0xf bound_ctrl:1
	v_cndmask_b32_e64 v58, v57, v56, s[42:43]
	v_cndmask_b32_e64 v56, v56, v57, s[42:43]
	v_mov_b32_e32 v57, v35
	v_mov_b32_e32 v59, v35
	s_nop 0
	v_mov_b32_dpp v57, v58 row_ror:4 row_mask:0xf bank_mask:0xf
	v_mov_b32_dpp v59, v58 row_ror:12 row_mask:0xf bank_mask:0xf
	v_cndmask_b32_e64 v57, v57, v59, s[42:43]
	v_add_f32_e32 v56, v56, v57
	v_mov_b32_e32 v57, 0
	s_nop 0
	v_add_f32_dpp v56, v56, v56 quad_perm:[2,3,0,1] row_mask:0xf bank_mask:0xf bound_ctrl:1
	s_nop 1
	v_mov_b32_dpp v57, v56 quad_perm:[1,0,3,2] row_mask:0xf bank_mask:0xf
	s_and_saveexec_b64 s[2:3], s[44:45]
	s_cbranch_execz .LBB0_1187
	v_add_f32_e32 v56, v56, v57
	v_add_f32_e32 v56, v34, v56
	v_exp_f32_e32 v56, v56
	v_add_u32_e32 v58, 0x80, v126
	v_add_f32_e32 v57, 1.0, v56
	v_rcp_f32_e32 v57, v57
	s_nop 0
	v_mul_f32_e32 v56, v56, v57
	ds_write2st64_b32 v58, v57, v56 offset0:4 offset1:68
.LBB0_1187:
	s_or_b64 exec, exec, s[2:3]
	s_waitcnt vmcnt(9)
	v_pk_mul_f32 v[56:57], v[6:7], v[48:49]
	s_nop 0
	v_pk_fma_f32 v[56:57], v[50:51], v[8:9], v[56:57]
	s_nop 0
	v_add_f32_e32 v58, v56, v57
	s_waitcnt vmcnt(8)
	v_pk_mul_f32 v[56:57], v[2:3], v[40:41]
	s_nop 0
	v_pk_fma_f32 v[56:57], v[42:43], v[4:5], v[56:57]
	s_nop 0
	v_add_f32_e32 v59, v56, v57
	v_pk_mul_f32 v[56:57], v[14:15], v[48:49]
	s_nop 0
	v_pk_fma_f32 v[56:57], v[50:51], v[16:17], v[56:57]
	s_nop 0
	v_add_f32_e32 v64, v56, v57
	v_pk_mul_f32 v[56:57], v[10:11], v[40:41]
	s_nop 0
	v_pk_fma_f32 v[56:57], v[42:43], v[12:13], v[56:57]
	s_nop 0
	v_add_f32_e32 v65, v56, v57
	v_pk_mul_f32 v[56:57], v[22:23], v[48:49]
	v_pk_mul_f32 v[48:49], v[30:31], v[48:49]
	v_pk_fma_f32 v[56:57], v[50:51], v[24:25], v[56:57]
	v_pk_fma_f32 v[48:49], v[50:51], v[32:33], v[48:49]
	v_add_f32_e32 v66, v56, v57
	v_add_f32_e32 v48, v48, v49
	v_pk_mul_f32 v[56:57], v[18:19], v[40:41]
	v_pk_mul_f32 v[40:41], v[26:27], v[40:41]
	v_pk_fma_f32 v[56:57], v[42:43], v[20:21], v[56:57]
	v_pk_fma_f32 v[40:41], v[42:43], v[28:29], v[40:41]
	v_add_f32_e32 v56, v56, v57
	v_add_f32_e32 v40, v40, v41
	s_waitcnt lgkmcnt(0)
	s_nop 1
	v_permlane16_swap_b32 v58, v66
	v_add_f32_e32 v41, v58, v66
	s_waitcnt lgkmcnt(2)
	s_nop 1
	v_permlane16_swap_b32 v59, v56
	v_add_f32_e32 v42, v59, v56
	s_waitcnt lgkmcnt(1)
	s_nop 1
	v_permlane16_swap_b32 v64, v48
	v_add_f32_e32 v43, v64, v48
	s_waitcnt lgkmcnt(0)
	s_nop 1
	v_permlane16_swap_b32 v65, v40
	v_add_f32_e32 v40, v65, v40
	v_cndmask_b32_e64 v48, v41, v43, s[38:39]
	v_cndmask_b32_e64 v41, v43, v41, s[38:39]
	v_cndmask_b32_e64 v43, v42, v40, s[38:39]
	v_cndmask_b32_e64 v40, v40, v42, s[38:39]
	v_add_f32_dpp v41, v48, v41 row_ror:8 row_mask:0xf bank_mask:0xf bound_ctrl:1
	s_nop 0
	v_add_f32_dpp v40, v43, v40 row_ror:8 row_mask:0xf bank_mask:0xf bound_ctrl:1
	v_cndmask_b32_e64 v42, v41, v40, s[42:43]
	v_cndmask_b32_e64 v40, v40, v41, s[42:43]
	v_mov_b32_e32 v41, v35
	v_mov_b32_e32 v43, v35
	s_nop 0
	v_mov_b32_dpp v41, v42 row_ror:4 row_mask:0xf bank_mask:0xf
	v_mov_b32_dpp v43, v42 row_ror:12 row_mask:0xf bank_mask:0xf
	v_cndmask_b32_e64 v41, v41, v43, s[42:43]
	v_add_f32_e32 v40, v40, v41
	v_mov_b32_e32 v41, 0
	s_nop 0
	v_add_f32_dpp v40, v40, v40 quad_perm:[2,3,0,1] row_mask:0xf bank_mask:0xf bound_ctrl:1
	s_nop 1
	v_mov_b32_dpp v41, v40 quad_perm:[1,0,3,2] row_mask:0xf bank_mask:0xf
	s_and_saveexec_b64 s[2:3], s[44:45]
	s_cbranch_execz .LBB0_1189
	v_add_f32_e32 v40, v40, v41
	v_add_f32_e32 v40, v34, v40
	v_exp_f32_e32 v40, v40
	v_add_u32_e32 v42, 0xc0, v126
	v_add_f32_e32 v41, 1.0, v40
	v_rcp_f32_e32 v41, v41
	s_nop 0
	v_mul_f32_e32 v40, v40, v41
	ds_write2st64_b32 v42, v41, v40 offset0:4 offset1:68
; #define DEC_LOADK(dst, i0) do { asm volatile("" ::: "memory"); _Pragma("unroll") for (int u = 0; u < 4; ++u) { const float* kr = ck + rbase + (size_t)((i0) + u) * 512; dst[u][0] = __builtin_nontemporal_load((const f32x4*)(kr + 4 * lane)); dst[u][1] = __builtin_nontemporal_load((const f32x4*)(kr + 256 + 4 * lane)); } } while (0)
; __device__ __forceinline__ void decode_item(Frame& F, const Args& a, int l, int item, unsigned char* ws) {
;     ...
;         DEC_LOADK(ka, 0); DEC_LOADK(kb, 4); DEC_SCORE(ka, 0); DEC_LOADK(ka, 8); DEC_SCORE(kb, 4); DEC_LOADK(kb, 12); DEC_SCORE(ka, 8); DEC_LOADK(ka, 16); DEC_SCORE(kb, 12); DEC_LOADK(kb, 20); DEC_SCORE(ka, 16); DEC_LOADK(ka, 24); DEC_SCORE(kb, 20); DEC_LOADK(kb, 28); DEC_SCORE(ka, 24); DEC_SCORE(kb, 28);
.LBB0_1189:
	s_or_b64 exec, exec, s[2:3]
	v_add_co_u32_e32 v40, vcc, 0xc000, v120
	s_waitcnt vmcnt(7)
	v_pk_mul_f32 v[100:101], v[6:7], v[92:93]
	v_addc_co_u32_e32 v41, vcc, 0, v121, vcc
	global_load_dwordx4 v[96:99], v[40:41], off nt
	global_load_dwordx4 v[88:91], v[40:41], off offset:1024 nt
	global_load_dwordx4 v[76:79], v[40:41], off offset:2048 nt
	global_load_dwordx4 v[68:71], v[40:41], off offset:3072 nt
	v_add_co_u32_e32 v40, vcc, 0xd000, v120
	v_pk_fma_f32 v[100:101], v[94:95], v[8:9], v[100:101]
	s_nop 0
	v_addc_co_u32_e32 v41, vcc, 0, v121, vcc
	global_load_dwordx4 v[64:67], v[40:41], off nt
	global_load_dwordx4 v[56:59], v[40:41], off offset:1024 nt
	global_load_dwordx4 v[48:51], v[40:41], off offset:2048 nt
	s_nop 0
	global_load_dwordx4 v[40:43], v[40:41], off offset:3072 nt
	v_add_f32_e32 v102, v100, v101
	s_waitcnt vmcnt(14)
	v_pk_mul_f32 v[100:101], v[2:3], v[84:85]
	s_nop 0
	v_pk_fma_f32 v[100:101], v[86:87], v[4:5], v[100:101]
	s_nop 0
	v_add_f32_e32 v103, v100, v101
	v_pk_mul_f32 v[100:101], v[14:15], v[92:93]
	s_nop 0
	v_pk_fma_f32 v[100:101], v[94:95], v[16:17], v[100:101]
	s_nop 0
	v_add_f32_e32 v104, v100, v101
	v_pk_mul_f32 v[100:101], v[10:11], v[84:85]
	s_nop 0
	v_pk_fma_f32 v[100:101], v[86:87], v[12:13], v[100:101]
	s_nop 0
	v_add_f32_e32 v105, v100, v101
	v_pk_mul_f32 v[100:101], v[22:23], v[92:93]
	v_pk_mul_f32 v[92:93], v[30:31], v[92:93]
	v_pk_fma_f32 v[100:101], v[94:95], v[24:25], v[100:101]
	v_pk_fma_f32 v[92:93], v[94:95], v[32:33], v[92:93]
	v_add_f32_e32 v106, v100, v101
	v_add_f32_e32 v92, v92, v93
	v_pk_mul_f32 v[100:101], v[18:19], v[84:85]
	v_pk_mul_f32 v[84:85], v[26:27], v[84:85]
	v_pk_fma_f32 v[100:101], v[86:87], v[20:21], v[100:101]
	v_pk_fma_f32 v[84:85], v[86:87], v[28:29], v[84:85]
	v_add_f32_e32 v100, v100, v101
	v_add_f32_e32 v84, v84, v85
	s_waitcnt lgkmcnt(0)
	s_nop 1
	v_permlane16_swap_b32 v102, v106
	v_add_f32_e32 v85, v102, v106
	s_waitcnt lgkmcnt(2)
	s_nop 1
	v_permlane16_swap_b32 v103, v100
	v_add_f32_e32 v86, v103, v100
	s_waitcnt lgkmcnt(1)
	s_nop 1
	v_permlane16_swap_b32 v104, v92
	v_add_f32_e32 v87, v104, v92
	s_waitcnt lgkmcnt(0)
	s_nop 1
	v_permlane16_swap_b32 v105, v84
	v_add_f32_e32 v84, v105, v84
	v_cndmask_b32_e64 v92, v85, v87, s[38:39]
	v_cndmask_b32_e64 v85, v87, v85, s[38:39]
	v_cndmask_b32_e64 v87, v86, v84, s[38:39]
	v_cndmask_b32_e64 v84, v84, v86, s[38:39]
	v_add_f32_dpp v85, v92, v85 row_ror:8 row_mask:0xf bank_mask:0xf bound_ctrl:1
	s_nop 0
	v_add_f32_dpp v84, v87, v84 row_ror:8 row_mask:0xf bank_mask:0xf bound_ctrl:1
	v_cndmask_b32_e64 v86, v85, v84, s[42:43]
	v_cndmask_b32_e64 v84, v84, v85, s[42:43]
	v_mov_b32_e32 v85, v35
	v_mov_b32_e32 v87, v35
	s_nop 0
	v_mov_b32_dpp v85, v86 row_ror:4 row_mask:0xf bank_mask:0xf
	v_mov_b32_dpp v87, v86 row_ror:12 row_mask:0xf bank_mask:0xf
	v_cndmask_b32_e64 v85, v85, v87, s[42:43]
	v_add_f32_e32 v84, v84, v85
	v_mov_b32_e32 v85, 0
	s_nop 0
	v_add_f32_dpp v84, v84, v84 quad_perm:[2,3,0,1] row_mask:0xf bank_mask:0xf bound_ctrl:1
	s_nop 1
	v_mov_b32_dpp v85, v84 quad_perm:[1,0,3,2] row_mask:0xf bank_mask:0xf
	s_and_saveexec_b64 s[2:3], s[44:45]
	s_cbranch_execz .LBB0_1191
	v_add_f32_e32 v84, v84, v85
	v_add_f32_e32 v84, v34, v84
	v_exp_f32_e32 v84, v84
	s_nop 0
	v_add_f32_e32 v85, 1.0, v84
	v_rcp_f32_e32 v85, v85
	s_nop 0
	v_mul_f32_e32 v84, v84, v85
	ds_write2st64_b32 v126, v85, v84 offset0:5 offset1:69
.LBB0_1191:
	s_or_b64 exec, exec, s[2:3]
	s_waitcnt vmcnt(13)
	v_pk_mul_f32 v[84:85], v[6:7], v[80:81]
	s_nop 0
	v_pk_fma_f32 v[84:85], v[82:83], v[8:9], v[84:85]
	s_nop 0
	v_add_f32_e32 v86, v84, v85
	s_waitcnt vmcnt(12)
	v_pk_mul_f32 v[84:85], v[2:3], v[72:73]
	s_nop 0
	v_pk_fma_f32 v[84:85], v[74:75], v[4:5], v[84:85]
	s_nop 0
	v_add_f32_e32 v87, v84, v85
	v_pk_mul_f32 v[84:85], v[14:15], v[80:81]
	s_nop 0
	v_pk_fma_f32 v[84:85], v[82:83], v[16:17], v[84:85]
	s_nop 0
	v_add_f32_e32 v92, v84, v85
	v_pk_mul_f32 v[84:85], v[10:11], v[72:73]
	s_nop 0
	v_pk_fma_f32 v[84:85], v[74:75], v[12:13], v[84:85]
	s_nop 0
	v_add_f32_e32 v93, v84, v85
	v_pk_mul_f32 v[84:85], v[22:23], v[80:81]
	v_pk_mul_f32 v[80:81], v[30:31], v[80:81]
	v_pk_fma_f32 v[84:85], v[82:83], v[24:25], v[84:85]
	v_pk_fma_f32 v[80:81], v[82:83], v[32:33], v[80:81]
	v_add_f32_e32 v94, v84, v85
	v_add_f32_e32 v80, v80, v81
	v_pk_mul_f32 v[84:85], v[18:19], v[72:73]
	v_pk_mul_f32 v[72:73], v[26:27], v[72:73]
	v_pk_fma_f32 v[84:85], v[74:75], v[20:21], v[84:85]
	v_pk_fma_f32 v[72:73], v[74:75], v[28:29], v[72:73]
	v_add_f32_e32 v84, v84, v85
	v_add_f32_e32 v72, v72, v73
	s_waitcnt lgkmcnt(0)
	s_nop 1
	v_permlane16_swap_b32 v86, v94
	v_add_f32_e32 v73, v86, v94
	s_waitcnt lgkmcnt(2)
	s_nop 1
	v_permlane16_swap_b32 v87, v84
	v_add_f32_e32 v74, v87, v84
	s_waitcnt lgkmcnt(1)
	s_nop 1
	v_permlane16_swap_b32 v92, v80
	v_add_f32_e32 v75, v92, v80
	s_waitcnt lgkmcnt(0)
	s_nop 1
	v_permlane16_swap_b32 v93, v72
	v_add_f32_e32 v72, v93, v72
	v_cndmask_b32_e64 v80, v73, v75, s[38:39]
	v_cndmask_b32_e64 v73, v75, v73, s[38:39]
	v_cndmask_b32_e64 v75, v74, v72, s[38:39]
	v_cndmask_b32_e64 v72, v72, v74, s[38:39]
	v_add_f32_dpp v73, v80, v73 row_ror:8 row_mask:0xf bank_mask:0xf bound_ctrl:1
	s_nop 0
	v_add_f32_dpp v72, v75, v72 row_ror:8 row_mask:0xf bank_mask:0xf bound_ctrl:1
	v_cndmask_b32_e64 v74, v73, v72, s[42:43]
	v_cndmask_b32_e64 v72, v72, v73, s[42:43]
	v_mov_b32_e32 v73, v35
	v_mov_b32_e32 v75, v35
	s_nop 0
	v_mov_b32_dpp v73, v74 row_ror:4 row_mask:0xf bank_mask:0xf
	v_mov_b32_dpp v75, v74 row_ror:12 row_mask:0xf bank_mask:0xf
	v_cndmask_b32_e64 v73, v73, v75, s[42:43]
	v_add_f32_e32 v72, v72, v73
	v_mov_b32_e32 v73, 0
	s_nop 0
	v_add_f32_dpp v72, v72, v72 quad_perm:[2,3,0,1] row_mask:0xf bank_mask:0xf bound_ctrl:1
	s_nop 1
	v_mov_b32_dpp v73, v72 quad_perm:[1,0,3,2] row_mask:0xf bank_mask:0xf
	s_and_saveexec_b64 s[2:3], s[44:45]
	s_cbranch_execz .LBB0_1193
	v_add_f32_e32 v72, v72, v73
	v_add_f32_e32 v72, v34, v72
	v_exp_f32_e32 v72, v72
	v_add_u32_e32 v74, 64, v126
	v_add_f32_e32 v73, 1.0, v72
	v_rcp_f32_e32 v73, v73
	s_nop 0
	v_mul_f32_e32 v72, v72, v73
	ds_write2st64_b32 v74, v73, v72 offset0:5 offset1:69
.LBB0_1193:
	s_or_b64 exec, exec, s[2:3]
	s_waitcnt vmcnt(11)
	v_pk_mul_f32 v[72:73], v[6:7], v[60:61]
	s_nop 0
	v_pk_fma_f32 v[72:73], v[62:63], v[8:9], v[72:73]
	s_nop 0
	v_add_f32_e32 v74, v72, v73
	s_waitcnt vmcnt(10)
	v_pk_mul_f32 v[72:73], v[2:3], v[52:53]
	s_nop 0
	v_pk_fma_f32 v[72:73], v[54:55], v[4:5], v[72:73]
	s_nop 0
	v_add_f32_e32 v75, v72, v73
	v_pk_mul_f32 v[72:73], v[14:15], v[60:61]
	s_nop 0
	v_pk_fma_f32 v[72:73], v[62:63], v[16:17], v[72:73]
	s_nop 0
	v_add_f32_e32 v80, v72, v73
	v_pk_mul_f32 v[72:73], v[10:11], v[52:53]
	s_nop 0
	v_pk_fma_f32 v[72:73], v[54:55], v[12:13], v[72:73]
	s_nop 0
	v_add_f32_e32 v81, v72, v73
	v_pk_mul_f32 v[72:73], v[22:23], v[60:61]
	v_pk_mul_f32 v[60:61], v[30:31], v[60:61]
	v_pk_fma_f32 v[72:73], v[62:63], v[24:25], v[72:73]
	v_pk_fma_f32 v[60:61], v[62:63], v[32:33], v[60:61]
	v_add_f32_e32 v82, v72, v73
	v_add_f32_e32 v60, v60, v61
	v_pk_mul_f32 v[72:73], v[18:19], v[52:53]
	v_pk_mul_f32 v[52:53], v[26:27], v[52:53]
	v_pk_fma_f32 v[72:73], v[54:55], v[20:21], v[72:73]
	v_pk_fma_f32 v[52:53], v[54:55], v[28:29], v[52:53]
	v_add_f32_e32 v72, v72, v73
	v_add_f32_e32 v52, v52, v53
	s_waitcnt lgkmcnt(0)
	s_nop 1
	v_permlane16_swap_b32 v74, v82
	v_add_f32_e32 v53, v74, v82
	s_waitcnt lgkmcnt(2)
	s_nop 1
	v_permlane16_swap_b32 v75, v72
	v_add_f32_e32 v54, v75, v72
	s_waitcnt lgkmcnt(1)
	s_nop 1
	v_permlane16_swap_b32 v80, v60
	v_add_f32_e32 v55, v80, v60
	s_waitcnt lgkmcnt(0)
	s_nop 1
	v_permlane16_swap_b32 v81, v52
	v_add_f32_e32 v52, v81, v52
	v_cndmask_b32_e64 v60, v53, v55, s[38:39]
	v_cndmask_b32_e64 v53, v55, v53, s[38:39]
	v_cndmask_b32_e64 v55, v54, v52, s[38:39]
	v_cndmask_b32_e64 v52, v52, v54, s[38:39]
	v_add_f32_dpp v53, v60, v53 row_ror:8 row_mask:0xf bank_mask:0xf bound_ctrl:1
	s_nop 0
	v_add_f32_dpp v52, v55, v52 row_ror:8 row_mask:0xf bank_mask:0xf bound_ctrl:1
	v_cndmask_b32_e64 v54, v53, v52, s[42:43]
	v_cndmask_b32_e64 v52, v52, v53, s[42:43]
	v_mov_b32_e32 v53, v35
	v_mov_b32_e32 v55, v35
	s_nop 0
	v_mov_b32_dpp v53, v54 row_ror:4 row_mask:0xf bank_mask:0xf
	v_mov_b32_dpp v55, v54 row_ror:12 row_mask:0xf bank_mask:0xf
	v_cndmask_b32_e64 v53, v53, v55, s[42:43]
	v_add_f32_e32 v52, v52, v53
	v_mov_b32_e32 v53, 0
	s_nop 0
	v_add_f32_dpp v52, v52, v52 quad_perm:[2,3,0,1] row_mask:0xf bank_mask:0xf bound_ctrl:1
	s_nop 1
	v_mov_b32_dpp v53, v52 quad_perm:[1,0,3,2] row_mask:0xf bank_mask:0xf
	s_and_saveexec_b64 s[2:3], s[44:45]
	s_cbranch_execz .LBB0_1195
	v_add_f32_e32 v52, v52, v53
	v_add_f32_e32 v52, v34, v52
	v_exp_f32_e32 v52, v52
	v_add_u32_e32 v54, 0x80, v126
	v_add_f32_e32 v53, 1.0, v52
	v_rcp_f32_e32 v53, v53
	s_nop 0
	v_mul_f32_e32 v52, v52, v53
	ds_write2st64_b32 v54, v53, v52 offset0:5 offset1:69
.LBB0_1195:
	s_or_b64 exec, exec, s[2:3]
	s_waitcnt vmcnt(9)
	v_pk_mul_f32 v[52:53], v[6:7], v[44:45]
	s_nop 0
	v_pk_fma_f32 v[52:53], v[46:47], v[8:9], v[52:53]
	s_nop 0
	v_add_f32_e32 v54, v52, v53
	s_waitcnt vmcnt(8)
	v_pk_mul_f32 v[52:53], v[2:3], v[36:37]
	s_nop 0
	v_pk_fma_f32 v[52:53], v[38:39], v[4:5], v[52:53]
	s_nop 0
	v_add_f32_e32 v55, v52, v53
	v_pk_mul_f32 v[52:53], v[14:15], v[44:45]
	s_nop 0
	v_pk_fma_f32 v[52:53], v[46:47], v[16:17], v[52:53]
	s_nop 0
	v_add_f32_e32 v60, v52, v53
	v_pk_mul_f32 v[52:53], v[10:11], v[36:37]
	s_nop 0
	v_pk_fma_f32 v[52:53], v[38:39], v[12:13], v[52:53]
	s_nop 0
	v_add_f32_e32 v61, v52, v53
	v_pk_mul_f32 v[52:53], v[22:23], v[44:45]
	v_pk_mul_f32 v[44:45], v[30:31], v[44:45]
	v_pk_fma_f32 v[52:53], v[46:47], v[24:25], v[52:53]
	v_pk_fma_f32 v[44:45], v[46:47], v[32:33], v[44:45]
	v_add_f32_e32 v62, v52, v53
	v_add_f32_e32 v44, v44, v45
	v_pk_mul_f32 v[52:53], v[18:19], v[36:37]
	v_pk_mul_f32 v[36:37], v[26:27], v[36:37]
	v_pk_fma_f32 v[52:53], v[38:39], v[20:21], v[52:53]
	v_pk_fma_f32 v[36:37], v[38:39], v[28:29], v[36:37]
	v_add_f32_e32 v52, v52, v53
	v_add_f32_e32 v36, v36, v37
	s_waitcnt lgkmcnt(0)
	s_nop 1
	v_permlane16_swap_b32 v54, v62
	v_add_f32_e32 v37, v54, v62
	s_waitcnt lgkmcnt(2)
	s_nop 1
	v_permlane16_swap_b32 v55, v52
	v_add_f32_e32 v38, v55, v52
	s_waitcnt lgkmcnt(1)
	s_nop 1
	v_permlane16_swap_b32 v60, v44
	v_add_f32_e32 v39, v60, v44
	s_waitcnt lgkmcnt(0)
	s_nop 1
	v_permlane16_swap_b32 v61, v36
	v_add_f32_e32 v36, v61, v36
	v_cndmask_b32_e64 v44, v37, v39, s[38:39]
	v_cndmask_b32_e64 v37, v39, v37, s[38:39]
	v_cndmask_b32_e64 v39, v38, v36, s[38:39]
	v_cndmask_b32_e64 v36, v36, v38, s[38:39]
	v_add_f32_dpp v37, v44, v37 row_ror:8 row_mask:0xf bank_mask:0xf bound_ctrl:1
	s_nop 0
	v_add_f32_dpp v36, v39, v36 row_ror:8 row_mask:0xf bank_mask:0xf bound_ctrl:1
	v_cndmask_b32_e64 v38, v37, v36, s[42:43]
	v_cndmask_b32_e64 v36, v36, v37, s[42:43]
	v_mov_b32_e32 v37, v35
	v_mov_b32_e32 v39, v35
	s_nop 0
	v_mov_b32_dpp v37, v38 row_ror:4 row_mask:0xf bank_mask:0xf
	v_mov_b32_dpp v39, v38 row_ror:12 row_mask:0xf bank_mask:0xf
	v_cndmask_b32_e64 v37, v37, v39, s[42:43]
	v_add_f32_e32 v36, v36, v37
	v_mov_b32_e32 v37, 0
	s_nop 0
	v_add_f32_dpp v36, v36, v36 quad_perm:[2,3,0,1] row_mask:0xf bank_mask:0xf bound_ctrl:1
	s_nop 1
	v_mov_b32_dpp v37, v36 quad_perm:[1,0,3,2] row_mask:0xf bank_mask:0xf
	s_and_saveexec_b64 s[2:3], s[44:45]
	s_cbranch_execz .LBB0_1197
	v_add_f32_e32 v36, v36, v37
	v_add_f32_e32 v36, v34, v36
	v_exp_f32_e32 v36, v36
	v_add_u32_e32 v38, 0xc0, v126
	v_add_f32_e32 v37, 1.0, v36
	v_rcp_f32_e32 v37, v37
	s_nop 0
	v_mul_f32_e32 v36, v36, v37
	ds_write2st64_b32 v38, v37, v36 offset0:5 offset1:69
